# scan waves: counted staged waits in step 0 of every batch (A, then K+VV, then W, then B) instead of waiting for all 11 LDS reads after the batch barrier
# baseline (speedup 1.0000x reference)
.LBB0_650:
	s_andn2_saveexec_b64 s[46:47], s[46:47]
	s_cbranch_execz .LBB0_652
	v_add_u32_e32 v136, 0xa000, v95
	ds_read_b128 v[28:31], v92 offset:256
	ds_read_b128 v[102:105], v92 offset:768
	ds_read2_b32 v[130:131], v136 offset0:0 offset1:16
	ds_read_b128 v[24:27], v92 offset:0
	ds_read_b128 v[98:101], v92 offset:512
	ds_read_b128 v[106:109], v92 offset:1024
	ds_read_b128 v[114:117], v92 offset:1536
	ds_read_b128 v[122:125], v92 offset:2048
	ds_read_b128 v[110:113], v92 offset:1280
	ds_read_b128 v[118:121], v92 offset:1792
	ds_read_b128 v[126:129], v92 offset:2304
	s_waitcnt lgkmcnt(10)
	v_pk_mul_f32 v[36:37], v[90:91], v[28:29]
	v_pk_fma_f32 v[36:37], v[88:89], v[30:31], v[36:37]
	v_add_f32_e32 v38, v36, v37
	s_waitcnt lgkmcnt(8)
	v_pk_mul_f32 v[40:41], v[102:103], v[130:131] op_sel_hi:[1,0]
	v_pk_mul_f32 v[42:43], v[104:105], v[130:131] op_sel_hi:[1,0]
	v_add_f32_dpp v38, v38, v38 quad_perm:[1,0,3,2] row_mask:0xf bank_mask:0xf bound_ctrl:1
	s_waitcnt lgkmcnt(7)
	v_pk_fma_f32 v[40:41], v[90:91], v[24:25], v[40:41]
	v_pk_fma_f32 v[42:43], v[88:89], v[26:27], v[42:43]
	v_add_f32_dpp v38, v38, v38 quad_perm:[2,3,0,1] row_mask:0xf bank_mask:0xf bound_ctrl:1
	s_nop 1
	v_add_f32_dpp v38, v38, v38 row_half_mirror row_mask:0xf bank_mask:0xf bound_ctrl:1
	s_waitcnt lgkmcnt(6)
	s_nop 0
	v_add_f32_dpp v38, v38, v38 row_mirror row_mask:0xf bank_mask:0xf bound_ctrl:1
	v_pk_fma_f32 v[90:91], v[98:99], v[38:39], v[40:41] op_sel_hi:[1,0,1]
	v_pk_fma_f32 v[88:89], v[100:101], v[38:39], v[42:43] op_sel_hi:[1,0,1]
	ds_read_b128 v[28:31], v92 offset:2816
	ds_read_b128 v[102:105], v92 offset:3328
	ds_read_b128 v[24:27], v92 offset:2560
	ds_read_b128 v[98:101], v92 offset:3072
	ds_read_b128 v[50:53], v92 offset:3584
	ds_read2_b32 v[132:133], v136 offset0:32 offset1:48
	s_waitcnt lgkmcnt(6)
	v_pk_mul_f32 v[36:37], v[90:91], v[114:115]
	v_pk_fma_f32 v[36:37], v[88:89], v[116:117], v[36:37]
	v_add_f32_e32 v38, v36, v37
	v_pk_mul_f32 v[40:41], v[122:123], v[130:131] op_sel:[0,1] op_sel_hi:[1,1]
	v_pk_mul_f32 v[42:43], v[124:125], v[130:131] op_sel:[0,1] op_sel_hi:[1,1]
	v_add_f32_dpp v38, v38, v38 quad_perm:[1,0,3,2] row_mask:0xf bank_mask:0xf bound_ctrl:1
	v_pk_fma_f32 v[40:41], v[90:91], v[110:111], v[40:41]
	v_pk_fma_f32 v[42:43], v[88:89], v[112:113], v[42:43]
	v_add_f32_dpp v38, v38, v38 quad_perm:[2,3,0,1] row_mask:0xf bank_mask:0xf bound_ctrl:1
	v_pk_mul_f32 v[44:45], v[90:91], v[106:107]
	v_pk_fma_f32 v[44:45], v[88:89], v[108:109], v[44:45]
	v_add_f32_dpp v38, v38, v38 row_half_mirror row_mask:0xf bank_mask:0xf bound_ctrl:1
	v_add_f32_e32 v46, v44, v45
	s_nop 0
	v_add_f32_dpp v38, v38, v38 row_mirror row_mask:0xf bank_mask:0xf bound_ctrl:1
	v_pk_fma_f32 v[90:91], v[118:119], v[38:39], v[40:41] op_sel_hi:[1,0,1]
	v_pk_fma_f32 v[88:89], v[120:121], v[38:39], v[42:43] op_sel_hi:[1,0,1]
	ds_read_b128 v[114:117], v92 offset:4096
	ds_read_b128 v[122:125], v92 offset:4608
	ds_read_b128 v[110:113], v92 offset:3840
	ds_read_b128 v[118:121], v92 offset:4352
	ds_read_b128 v[54:57], v92 offset:4864
	s_waitcnt lgkmcnt(5)
	v_pk_mul_f32 v[36:37], v[90:91], v[28:29]
	v_pk_fma_f32 v[36:37], v[88:89], v[30:31], v[36:37]
	v_add_f32_e32 v38, v36, v37
	v_pk_mul_f32 v[40:41], v[102:103], v[132:133] op_sel_hi:[1,0]
	v_pk_mul_f32 v[42:43], v[104:105], v[132:133] op_sel_hi:[1,0]
	v_add_f32_dpp v38, v38, v38 quad_perm:[1,0,3,2] row_mask:0xf bank_mask:0xf bound_ctrl:1
	v_pk_fma_f32 v[40:41], v[90:91], v[24:25], v[40:41]
	v_pk_fma_f32 v[42:43], v[88:89], v[26:27], v[42:43]
	v_add_f32_dpp v38, v38, v38 quad_perm:[2,3,0,1] row_mask:0xf bank_mask:0xf bound_ctrl:1
	v_pk_mul_f32 v[44:45], v[90:91], v[126:127]
	v_pk_fma_f32 v[44:45], v[88:89], v[128:129], v[44:45]
	v_add_f32_dpp v38, v38, v38 row_half_mirror row_mask:0xf bank_mask:0xf bound_ctrl:1
	v_add_f32_e32 v47, v44, v45
	s_nop 0
	v_add_f32_dpp v38, v38, v38 row_mirror row_mask:0xf bank_mask:0xf bound_ctrl:1
	v_pk_fma_f32 v[90:91], v[98:99], v[38:39], v[40:41] op_sel_hi:[1,0,1]
	v_pk_fma_f32 v[88:89], v[100:101], v[38:39], v[42:43] op_sel_hi:[1,0,1]
	ds_read_b128 v[28:31], v92 offset:5376
	ds_read_b128 v[102:105], v92 offset:5888
	ds_read_b128 v[24:27], v92 offset:5120
	ds_read_b128 v[98:101], v92 offset:5632
	ds_read_b128 v[106:109], v92 offset:6144
	ds_read2_b32 v[130:131], v136 offset0:64 offset1:80
	ds_write2st64_b32 v96, v46, v47 offset0:168 offset1:172
	s_waitcnt lgkmcnt(7)
	v_pk_mul_f32 v[36:37], v[90:91], v[114:115]
	v_pk_fma_f32 v[36:37], v[88:89], v[116:117], v[36:37]
	v_add_f32_e32 v38, v36, v37
	v_pk_mul_f32 v[40:41], v[122:123], v[132:133] op_sel:[0,1] op_sel_hi:[1,1]
	v_pk_mul_f32 v[42:43], v[124:125], v[132:133] op_sel:[0,1] op_sel_hi:[1,1]
	v_add_f32_dpp v38, v38, v38 quad_perm:[1,0,3,2] row_mask:0xf bank_mask:0xf bound_ctrl:1
	v_pk_fma_f32 v[40:41], v[90:91], v[110:111], v[40:41]
	v_pk_fma_f32 v[42:43], v[88:89], v[112:113], v[42:43]
	v_add_f32_dpp v38, v38, v38 quad_perm:[2,3,0,1] row_mask:0xf bank_mask:0xf bound_ctrl:1
	v_pk_mul_f32 v[44:45], v[90:91], v[50:51]
	v_pk_fma_f32 v[44:45], v[88:89], v[52:53], v[44:45]
	v_add_f32_dpp v38, v38, v38 row_half_mirror row_mask:0xf bank_mask:0xf bound_ctrl:1
	v_add_f32_e32 v48, v44, v45
	s_nop 0
	v_add_f32_dpp v38, v38, v38 row_mirror row_mask:0xf bank_mask:0xf bound_ctrl:1
	v_pk_fma_f32 v[90:91], v[118:119], v[38:39], v[40:41] op_sel_hi:[1,0,1]
	v_pk_fma_f32 v[88:89], v[120:121], v[38:39], v[42:43] op_sel_hi:[1,0,1]
	ds_read_b128 v[114:117], v92 offset:6656
	ds_read_b128 v[122:125], v92 offset:7168
	ds_read_b128 v[110:113], v92 offset:6400
	ds_read_b128 v[118:121], v92 offset:6912
	ds_read_b128 v[126:129], v92 offset:7424
	s_waitcnt lgkmcnt(5)
	v_pk_mul_f32 v[36:37], v[90:91], v[28:29]
	v_pk_fma_f32 v[36:37], v[88:89], v[30:31], v[36:37]
	v_add_f32_e32 v38, v36, v37
	v_pk_mul_f32 v[40:41], v[102:103], v[130:131] op_sel_hi:[1,0]
	v_pk_mul_f32 v[42:43], v[104:105], v[130:131] op_sel_hi:[1,0]
	v_add_f32_dpp v38, v38, v38 quad_perm:[1,0,3,2] row_mask:0xf bank_mask:0xf bound_ctrl:1
	v_pk_fma_f32 v[40:41], v[90:91], v[24:25], v[40:41]
	v_pk_fma_f32 v[42:43], v[88:89], v[26:27], v[42:43]
	v_add_f32_dpp v38, v38, v38 quad_perm:[2,3,0,1] row_mask:0xf bank_mask:0xf bound_ctrl:1
	v_pk_mul_f32 v[44:45], v[90:91], v[54:55]
	v_pk_fma_f32 v[44:45], v[88:89], v[56:57], v[44:45]
	v_add_f32_dpp v38, v38, v38 row_half_mirror row_mask:0xf bank_mask:0xf bound_ctrl:1
	v_add_f32_e32 v49, v44, v45
	s_nop 0
	v_add_f32_dpp v38, v38, v38 row_mirror row_mask:0xf bank_mask:0xf bound_ctrl:1
	v_pk_fma_f32 v[90:91], v[98:99], v[38:39], v[40:41] op_sel_hi:[1,0,1]
	v_pk_fma_f32 v[88:89], v[100:101], v[38:39], v[42:43] op_sel_hi:[1,0,1]
	ds_read_b128 v[28:31], v92 offset:7936
	ds_read_b128 v[102:105], v92 offset:8448
	ds_read_b128 v[24:27], v92 offset:7680
	ds_read_b128 v[98:101], v92 offset:8192
	ds_read_b128 v[50:53], v92 offset:8704
	ds_read2_b32 v[132:133], v136 offset0:96 offset1:112
	ds_write2st64_b32 v96, v48, v49 offset0:176 offset1:180
	s_waitcnt lgkmcnt(7)
	v_pk_mul_f32 v[36:37], v[90:91], v[114:115]
	v_pk_fma_f32 v[36:37], v[88:89], v[116:117], v[36:37]
	v_add_f32_e32 v38, v36, v37
	v_pk_mul_f32 v[40:41], v[122:123], v[130:131] op_sel:[0,1] op_sel_hi:[1,1]
	v_pk_mul_f32 v[42:43], v[124:125], v[130:131] op_sel:[0,1] op_sel_hi:[1,1]
	v_add_f32_dpp v38, v38, v38 quad_perm:[1,0,3,2] row_mask:0xf bank_mask:0xf bound_ctrl:1
	v_pk_fma_f32 v[40:41], v[90:91], v[110:111], v[40:41]
	v_pk_fma_f32 v[42:43], v[88:89], v[112:113], v[42:43]
	v_add_f32_dpp v38, v38, v38 quad_perm:[2,3,0,1] row_mask:0xf bank_mask:0xf bound_ctrl:1
	v_pk_mul_f32 v[44:45], v[90:91], v[106:107]
	v_pk_fma_f32 v[44:45], v[88:89], v[108:109], v[44:45]
	v_add_f32_dpp v38, v38, v38 row_half_mirror row_mask:0xf bank_mask:0xf bound_ctrl:1
	v_add_f32_e32 v46, v44, v45
	s_nop 0
	v_add_f32_dpp v38, v38, v38 row_mirror row_mask:0xf bank_mask:0xf bound_ctrl:1
	v_pk_fma_f32 v[90:91], v[118:119], v[38:39], v[40:41] op_sel_hi:[1,0,1]
	v_pk_fma_f32 v[88:89], v[120:121], v[38:39], v[42:43] op_sel_hi:[1,0,1]
	ds_read_b128 v[114:117], v92 offset:9216
	ds_read_b128 v[122:125], v92 offset:9728
	ds_read_b128 v[110:113], v92 offset:8960
	ds_read_b128 v[118:121], v92 offset:9472
	ds_read_b128 v[54:57], v92 offset:9984
	s_waitcnt lgkmcnt(5)
	v_pk_mul_f32 v[36:37], v[90:91], v[28:29]
	v_pk_fma_f32 v[36:37], v[88:89], v[30:31], v[36:37]
	v_add_f32_e32 v38, v36, v37
	v_pk_mul_f32 v[40:41], v[102:103], v[132:133] op_sel_hi:[1,0]
	v_pk_mul_f32 v[42:43], v[104:105], v[132:133] op_sel_hi:[1,0]
	v_add_f32_dpp v38, v38, v38 quad_perm:[1,0,3,2] row_mask:0xf bank_mask:0xf bound_ctrl:1
	v_pk_fma_f32 v[40:41], v[90:91], v[24:25], v[40:41]
	v_pk_fma_f32 v[42:43], v[88:89], v[26:27], v[42:43]
	v_add_f32_dpp v38, v38, v38 quad_perm:[2,3,0,1] row_mask:0xf bank_mask:0xf bound_ctrl:1
	v_pk_mul_f32 v[44:45], v[90:91], v[126:127]
	v_pk_fma_f32 v[44:45], v[88:89], v[128:129], v[44:45]
	v_add_f32_dpp v38, v38, v38 row_half_mirror row_mask:0xf bank_mask:0xf bound_ctrl:1
	v_add_f32_e32 v47, v44, v45
	s_nop 0
	v_add_f32_dpp v38, v38, v38 row_mirror row_mask:0xf bank_mask:0xf bound_ctrl:1
	v_pk_fma_f32 v[90:91], v[98:99], v[38:39], v[40:41] op_sel_hi:[1,0,1]
	v_pk_fma_f32 v[88:89], v[100:101], v[38:39], v[42:43] op_sel_hi:[1,0,1]
	ds_read_b128 v[28:31], v92 offset:10496
	ds_read_b128 v[102:105], v92 offset:11008
	ds_read_b128 v[24:27], v92 offset:10240
	ds_read_b128 v[98:101], v92 offset:10752
	ds_read_b128 v[106:109], v92 offset:11264
	ds_read2_b32 v[130:131], v136 offset0:128 offset1:144
	ds_write2st64_b32 v96, v46, v47 offset0:184 offset1:188
	s_waitcnt lgkmcnt(7)
	v_pk_mul_f32 v[36:37], v[90:91], v[114:115]
	v_pk_fma_f32 v[36:37], v[88:89], v[116:117], v[36:37]
	v_add_f32_e32 v38, v36, v37
	v_pk_mul_f32 v[40:41], v[122:123], v[132:133] op_sel:[0,1] op_sel_hi:[1,1]
	v_pk_mul_f32 v[42:43], v[124:125], v[132:133] op_sel:[0,1] op_sel_hi:[1,1]
	v_add_f32_dpp v38, v38, v38 quad_perm:[1,0,3,2] row_mask:0xf bank_mask:0xf bound_ctrl:1
	v_pk_fma_f32 v[40:41], v[90:91], v[110:111], v[40:41]
	v_pk_fma_f32 v[42:43], v[88:89], v[112:113], v[42:43]
	v_add_f32_dpp v38, v38, v38 quad_perm:[2,3,0,1] row_mask:0xf bank_mask:0xf bound_ctrl:1
	v_pk_mul_f32 v[44:45], v[90:91], v[50:51]
	v_pk_fma_f32 v[44:45], v[88:89], v[52:53], v[44:45]
	v_add_f32_dpp v38, v38, v38 row_half_mirror row_mask:0xf bank_mask:0xf bound_ctrl:1
	v_add_f32_e32 v48, v44, v45
	s_nop 0
	v_add_f32_dpp v38, v38, v38 row_mirror row_mask:0xf bank_mask:0xf bound_ctrl:1
	v_pk_fma_f32 v[90:91], v[118:119], v[38:39], v[40:41] op_sel_hi:[1,0,1]
	v_pk_fma_f32 v[88:89], v[120:121], v[38:39], v[42:43] op_sel_hi:[1,0,1]
	ds_read_b128 v[114:117], v92 offset:11776
	ds_read_b128 v[122:125], v92 offset:12288
	ds_read_b128 v[110:113], v92 offset:11520
	ds_read_b128 v[118:121], v92 offset:12032
	ds_read_b128 v[126:129], v92 offset:12544
	s_waitcnt lgkmcnt(5)
	v_pk_mul_f32 v[36:37], v[90:91], v[28:29]
	v_pk_fma_f32 v[36:37], v[88:89], v[30:31], v[36:37]
	v_add_f32_e32 v38, v36, v37
	v_pk_mul_f32 v[40:41], v[102:103], v[130:131] op_sel_hi:[1,0]
	v_pk_mul_f32 v[42:43], v[104:105], v[130:131] op_sel_hi:[1,0]
	v_add_f32_dpp v38, v38, v38 quad_perm:[1,0,3,2] row_mask:0xf bank_mask:0xf bound_ctrl:1
	v_pk_fma_f32 v[40:41], v[90:91], v[24:25], v[40:41]
	v_pk_fma_f32 v[42:43], v[88:89], v[26:27], v[42:43]
	v_add_f32_dpp v38, v38, v38 quad_perm:[2,3,0,1] row_mask:0xf bank_mask:0xf bound_ctrl:1
	v_pk_mul_f32 v[44:45], v[90:91], v[54:55]
	v_pk_fma_f32 v[44:45], v[88:89], v[56:57], v[44:45]
	v_add_f32_dpp v38, v38, v38 row_half_mirror row_mask:0xf bank_mask:0xf bound_ctrl:1
	v_add_f32_e32 v49, v44, v45
	s_nop 0
	v_add_f32_dpp v38, v38, v38 row_mirror row_mask:0xf bank_mask:0xf bound_ctrl:1
	v_pk_fma_f32 v[90:91], v[98:99], v[38:39], v[40:41] op_sel_hi:[1,0,1]
	v_pk_fma_f32 v[88:89], v[100:101], v[38:39], v[42:43] op_sel_hi:[1,0,1]
	ds_read_b128 v[28:31], v92 offset:13056
	ds_read_b128 v[102:105], v92 offset:13568
	ds_read_b128 v[24:27], v92 offset:12800
	ds_read_b128 v[98:101], v92 offset:13312
	ds_read_b128 v[50:53], v92 offset:13824
	ds_read2_b32 v[132:133], v136 offset0:160 offset1:176
	ds_write2st64_b32 v96, v48, v49 offset0:192 offset1:196
	s_waitcnt lgkmcnt(7)
	v_pk_mul_f32 v[36:37], v[90:91], v[114:115]
	v_pk_fma_f32 v[36:37], v[88:89], v[116:117], v[36:37]
	v_add_f32_e32 v38, v36, v37
	v_pk_mul_f32 v[40:41], v[122:123], v[130:131] op_sel:[0,1] op_sel_hi:[1,1]
	v_pk_mul_f32 v[42:43], v[124:125], v[130:131] op_sel:[0,1] op_sel_hi:[1,1]
	v_add_f32_dpp v38, v38, v38 quad_perm:[1,0,3,2] row_mask:0xf bank_mask:0xf bound_ctrl:1
	v_pk_fma_f32 v[40:41], v[90:91], v[110:111], v[40:41]
	v_pk_fma_f32 v[42:43], v[88:89], v[112:113], v[42:43]
	v_add_f32_dpp v38, v38, v38 quad_perm:[2,3,0,1] row_mask:0xf bank_mask:0xf bound_ctrl:1
	v_pk_mul_f32 v[44:45], v[90:91], v[106:107]
	v_pk_fma_f32 v[44:45], v[88:89], v[108:109], v[44:45]
	v_add_f32_dpp v38, v38, v38 row_half_mirror row_mask:0xf bank_mask:0xf bound_ctrl:1
	v_add_f32_e32 v46, v44, v45
	s_nop 0
	v_add_f32_dpp v38, v38, v38 row_mirror row_mask:0xf bank_mask:0xf bound_ctrl:1
	v_pk_fma_f32 v[90:91], v[118:119], v[38:39], v[40:41] op_sel_hi:[1,0,1]
	v_pk_fma_f32 v[88:89], v[120:121], v[38:39], v[42:43] op_sel_hi:[1,0,1]
	ds_read_b128 v[114:117], v92 offset:14336
	ds_read_b128 v[122:125], v92 offset:14848
	ds_read_b128 v[110:113], v92 offset:14080
	ds_read_b128 v[118:121], v92 offset:14592
	ds_read_b128 v[54:57], v92 offset:15104
	s_waitcnt lgkmcnt(5)
	v_pk_mul_f32 v[36:37], v[90:91], v[28:29]
	v_pk_fma_f32 v[36:37], v[88:89], v[30:31], v[36:37]
	v_add_f32_e32 v38, v36, v37
	v_pk_mul_f32 v[40:41], v[102:103], v[132:133] op_sel_hi:[1,0]
	v_pk_mul_f32 v[42:43], v[104:105], v[132:133] op_sel_hi:[1,0]
	v_add_f32_dpp v38, v38, v38 quad_perm:[1,0,3,2] row_mask:0xf bank_mask:0xf bound_ctrl:1
	v_pk_fma_f32 v[40:41], v[90:91], v[24:25], v[40:41]
	v_pk_fma_f32 v[42:43], v[88:89], v[26:27], v[42:43]
	v_add_f32_dpp v38, v38, v38 quad_perm:[2,3,0,1] row_mask:0xf bank_mask:0xf bound_ctrl:1
	v_pk_mul_f32 v[44:45], v[90:91], v[126:127]
	v_pk_fma_f32 v[44:45], v[88:89], v[128:129], v[44:45]
	v_add_f32_dpp v38, v38, v38 row_half_mirror row_mask:0xf bank_mask:0xf bound_ctrl:1
	v_add_f32_e32 v47, v44, v45
	s_nop 0
	v_add_f32_dpp v38, v38, v38 row_mirror row_mask:0xf bank_mask:0xf bound_ctrl:1
	v_pk_fma_f32 v[90:91], v[98:99], v[38:39], v[40:41] op_sel_hi:[1,0,1]
	v_pk_fma_f32 v[88:89], v[100:101], v[38:39], v[42:43] op_sel_hi:[1,0,1]
	ds_read_b128 v[28:31], v92 offset:15616
	ds_read_b128 v[102:105], v92 offset:16128
	ds_read_b128 v[24:27], v92 offset:15360
	ds_read_b128 v[98:101], v92 offset:15872
	ds_read_b128 v[106:109], v92 offset:16384
	ds_read2_b32 v[130:131], v136 offset0:192 offset1:208
	ds_write2st64_b32 v96, v46, v47 offset0:200 offset1:204
	s_waitcnt lgkmcnt(7)
	v_pk_mul_f32 v[36:37], v[90:91], v[114:115]
	v_pk_fma_f32 v[36:37], v[88:89], v[116:117], v[36:37]
	v_add_f32_e32 v38, v36, v37
	v_pk_mul_f32 v[40:41], v[122:123], v[132:133] op_sel:[0,1] op_sel_hi:[1,1]
	v_pk_mul_f32 v[42:43], v[124:125], v[132:133] op_sel:[0,1] op_sel_hi:[1,1]
	v_add_f32_dpp v38, v38, v38 quad_perm:[1,0,3,2] row_mask:0xf bank_mask:0xf bound_ctrl:1
	v_pk_fma_f32 v[40:41], v[90:91], v[110:111], v[40:41]
	v_pk_fma_f32 v[42:43], v[88:89], v[112:113], v[42:43]
	v_add_f32_dpp v38, v38, v38 quad_perm:[2,3,0,1] row_mask:0xf bank_mask:0xf bound_ctrl:1
	v_pk_mul_f32 v[44:45], v[90:91], v[50:51]
	v_pk_fma_f32 v[44:45], v[88:89], v[52:53], v[44:45]
	v_add_f32_dpp v38, v38, v38 row_half_mirror row_mask:0xf bank_mask:0xf bound_ctrl:1
	v_add_f32_e32 v48, v44, v45
	s_nop 0
	v_add_f32_dpp v38, v38, v38 row_mirror row_mask:0xf bank_mask:0xf bound_ctrl:1
	v_pk_fma_f32 v[90:91], v[118:119], v[38:39], v[40:41] op_sel_hi:[1,0,1]
	v_pk_fma_f32 v[88:89], v[120:121], v[38:39], v[42:43] op_sel_hi:[1,0,1]
	ds_read_b128 v[114:117], v92 offset:16896
	ds_read_b128 v[122:125], v92 offset:17408
	ds_read_b128 v[110:113], v92 offset:16640
	ds_read_b128 v[118:121], v92 offset:17152
	ds_read_b128 v[126:129], v92 offset:17664
	s_waitcnt lgkmcnt(5)
	v_pk_mul_f32 v[36:37], v[90:91], v[28:29]
	v_pk_fma_f32 v[36:37], v[88:89], v[30:31], v[36:37]
	v_add_f32_e32 v38, v36, v37
	v_pk_mul_f32 v[40:41], v[102:103], v[130:131] op_sel_hi:[1,0]
	v_pk_mul_f32 v[42:43], v[104:105], v[130:131] op_sel_hi:[1,0]
	v_add_f32_dpp v38, v38, v38 quad_perm:[1,0,3,2] row_mask:0xf bank_mask:0xf bound_ctrl:1
	v_pk_fma_f32 v[40:41], v[90:91], v[24:25], v[40:41]
	v_pk_fma_f32 v[42:43], v[88:89], v[26:27], v[42:43]
	v_add_f32_dpp v38, v38, v38 quad_perm:[2,3,0,1] row_mask:0xf bank_mask:0xf bound_ctrl:1
	v_pk_mul_f32 v[44:45], v[90:91], v[54:55]
	v_pk_fma_f32 v[44:45], v[88:89], v[56:57], v[44:45]
	v_add_f32_dpp v38, v38, v38 row_half_mirror row_mask:0xf bank_mask:0xf bound_ctrl:1
	v_add_f32_e32 v49, v44, v45
	s_nop 0
	v_add_f32_dpp v38, v38, v38 row_mirror row_mask:0xf bank_mask:0xf bound_ctrl:1
	v_pk_fma_f32 v[90:91], v[98:99], v[38:39], v[40:41] op_sel_hi:[1,0,1]
	v_pk_fma_f32 v[88:89], v[100:101], v[38:39], v[42:43] op_sel_hi:[1,0,1]
	ds_read_b128 v[28:31], v92 offset:18176
	ds_read_b128 v[102:105], v92 offset:18688
	ds_read_b128 v[24:27], v92 offset:17920
	ds_read_b128 v[98:101], v92 offset:18432
	ds_read_b128 v[50:53], v92 offset:18944
	ds_read2_b32 v[132:133], v136 offset0:224 offset1:240
	ds_write2st64_b32 v96, v48, v49 offset0:208 offset1:212
	s_waitcnt lgkmcnt(7)
	v_pk_mul_f32 v[36:37], v[90:91], v[114:115]
	v_pk_fma_f32 v[36:37], v[88:89], v[116:117], v[36:37]
	v_add_f32_e32 v38, v36, v37
	v_pk_mul_f32 v[40:41], v[122:123], v[130:131] op_sel:[0,1] op_sel_hi:[1,1]
	v_pk_mul_f32 v[42:43], v[124:125], v[130:131] op_sel:[0,1] op_sel_hi:[1,1]
	v_add_f32_dpp v38, v38, v38 quad_perm:[1,0,3,2] row_mask:0xf bank_mask:0xf bound_ctrl:1
	v_pk_fma_f32 v[40:41], v[90:91], v[110:111], v[40:41]
	v_pk_fma_f32 v[42:43], v[88:89], v[112:113], v[42:43]
	v_add_f32_dpp v38, v38, v38 quad_perm:[2,3,0,1] row_mask:0xf bank_mask:0xf bound_ctrl:1
	v_pk_mul_f32 v[44:45], v[90:91], v[106:107]
	v_pk_fma_f32 v[44:45], v[88:89], v[108:109], v[44:45]
	v_add_f32_dpp v38, v38, v38 row_half_mirror row_mask:0xf bank_mask:0xf bound_ctrl:1
	v_add_f32_e32 v46, v44, v45
	s_nop 0
	v_add_f32_dpp v38, v38, v38 row_mirror row_mask:0xf bank_mask:0xf bound_ctrl:1
	v_pk_fma_f32 v[90:91], v[118:119], v[38:39], v[40:41] op_sel_hi:[1,0,1]
	v_pk_fma_f32 v[88:89], v[120:121], v[38:39], v[42:43] op_sel_hi:[1,0,1]
	ds_read_b128 v[114:117], v92 offset:19456
	ds_read_b128 v[122:125], v92 offset:19968
	ds_read_b128 v[110:113], v92 offset:19200
	ds_read_b128 v[118:121], v92 offset:19712
	ds_read_b128 v[54:57], v92 offset:20224
	s_waitcnt lgkmcnt(5)
	v_pk_mul_f32 v[36:37], v[90:91], v[28:29]
	v_pk_fma_f32 v[36:37], v[88:89], v[30:31], v[36:37]
	v_add_f32_e32 v38, v36, v37
	v_pk_mul_f32 v[40:41], v[102:103], v[132:133] op_sel_hi:[1,0]
	v_pk_mul_f32 v[42:43], v[104:105], v[132:133] op_sel_hi:[1,0]
	v_add_f32_dpp v38, v38, v38 quad_perm:[1,0,3,2] row_mask:0xf bank_mask:0xf bound_ctrl:1
	v_pk_fma_f32 v[40:41], v[90:91], v[24:25], v[40:41]
	v_pk_fma_f32 v[42:43], v[88:89], v[26:27], v[42:43]
	v_add_f32_dpp v38, v38, v38 quad_perm:[2,3,0,1] row_mask:0xf bank_mask:0xf bound_ctrl:1
	v_pk_mul_f32 v[44:45], v[90:91], v[126:127]
	v_pk_fma_f32 v[44:45], v[88:89], v[128:129], v[44:45]
	v_add_f32_dpp v38, v38, v38 row_half_mirror row_mask:0xf bank_mask:0xf bound_ctrl:1
	v_add_f32_e32 v47, v44, v45
	s_nop 0
	v_add_f32_dpp v38, v38, v38 row_mirror row_mask:0xf bank_mask:0xf bound_ctrl:1
	v_pk_fma_f32 v[90:91], v[98:99], v[38:39], v[40:41] op_sel_hi:[1,0,1]
	v_pk_fma_f32 v[88:89], v[100:101], v[38:39], v[42:43] op_sel_hi:[1,0,1]
	ds_write2st64_b32 v96, v46, v47 offset0:216 offset1:220
	s_waitcnt lgkmcnt(1)
	v_pk_mul_f32 v[36:37], v[90:91], v[114:115]
	v_pk_fma_f32 v[36:37], v[88:89], v[116:117], v[36:37]
	v_add_f32_e32 v38, v36, v37
	v_pk_mul_f32 v[40:41], v[122:123], v[132:133] op_sel:[0,1] op_sel_hi:[1,1]
	v_pk_mul_f32 v[42:43], v[124:125], v[132:133] op_sel:[0,1] op_sel_hi:[1,1]
	v_add_f32_dpp v38, v38, v38 quad_perm:[1,0,3,2] row_mask:0xf bank_mask:0xf bound_ctrl:1
	v_pk_fma_f32 v[40:41], v[90:91], v[110:111], v[40:41]
	v_pk_fma_f32 v[42:43], v[88:89], v[112:113], v[42:43]
	v_add_f32_dpp v38, v38, v38 quad_perm:[2,3,0,1] row_mask:0xf bank_mask:0xf bound_ctrl:1
	v_pk_mul_f32 v[44:45], v[90:91], v[50:51]
	v_pk_fma_f32 v[44:45], v[88:89], v[52:53], v[44:45]
	v_add_f32_dpp v38, v38, v38 row_half_mirror row_mask:0xf bank_mask:0xf bound_ctrl:1
	v_add_f32_e32 v48, v44, v45
	s_nop 0
	v_add_f32_dpp v38, v38, v38 row_mirror row_mask:0xf bank_mask:0xf bound_ctrl:1
	v_pk_fma_f32 v[90:91], v[118:119], v[38:39], v[40:41] op_sel_hi:[1,0,1]
	v_pk_fma_f32 v[88:89], v[120:121], v[38:39], v[42:43] op_sel_hi:[1,0,1]
	v_pk_mul_f32 v[44:45], v[90:91], v[54:55]
	v_pk_fma_f32 v[44:45], v[88:89], v[56:57], v[44:45]
	v_add_f32_e32 v49, v44, v45
	ds_write2st64_b32 v96, v48, v49 offset0:224 offset1:228

.LBB0_660:
	s_andn2_saveexec_b64 s[46:47], s[46:47]
	s_cbranch_execz .LBB0_640
	v_add_u32_e32 v136, 0xa400, v95
	ds_read_b128 v[28:31], v92 offset:20736
	ds_read_b128 v[102:105], v92 offset:21248
	ds_read2_b32 v[130:131], v136 offset0:0 offset1:16
	ds_read_b128 v[24:27], v92 offset:20480
	ds_read_b128 v[98:101], v92 offset:20992
	ds_read_b128 v[106:109], v92 offset:21504
	ds_read_b128 v[114:117], v92 offset:22016
	ds_read_b128 v[122:125], v92 offset:22528
	ds_read_b128 v[110:113], v92 offset:21760
	ds_read_b128 v[118:121], v92 offset:22272
	ds_read_b128 v[126:129], v92 offset:22784
	s_waitcnt lgkmcnt(10)
	v_pk_mul_f32 v[36:37], v[90:91], v[28:29]
	v_pk_fma_f32 v[36:37], v[88:89], v[30:31], v[36:37]
	v_add_f32_e32 v38, v36, v37
	s_waitcnt lgkmcnt(8)
	v_pk_mul_f32 v[40:41], v[102:103], v[130:131] op_sel_hi:[1,0]
	v_pk_mul_f32 v[42:43], v[104:105], v[130:131] op_sel_hi:[1,0]
	v_add_f32_dpp v38, v38, v38 quad_perm:[1,0,3,2] row_mask:0xf bank_mask:0xf bound_ctrl:1
	s_waitcnt lgkmcnt(7)
	v_pk_fma_f32 v[40:41], v[90:91], v[24:25], v[40:41]
	v_pk_fma_f32 v[42:43], v[88:89], v[26:27], v[42:43]
	v_add_f32_dpp v38, v38, v38 quad_perm:[2,3,0,1] row_mask:0xf bank_mask:0xf bound_ctrl:1
	s_nop 1
	v_add_f32_dpp v38, v38, v38 row_half_mirror row_mask:0xf bank_mask:0xf bound_ctrl:1
	s_waitcnt lgkmcnt(6)
	s_nop 0
	v_add_f32_dpp v38, v38, v38 row_mirror row_mask:0xf bank_mask:0xf bound_ctrl:1
	v_pk_fma_f32 v[90:91], v[98:99], v[38:39], v[40:41] op_sel_hi:[1,0,1]
	v_pk_fma_f32 v[88:89], v[100:101], v[38:39], v[42:43] op_sel_hi:[1,0,1]
	ds_read_b128 v[28:31], v92 offset:23296
	ds_read_b128 v[102:105], v92 offset:23808
	ds_read_b128 v[24:27], v92 offset:23040
	ds_read_b128 v[98:101], v92 offset:23552
	ds_read_b128 v[50:53], v92 offset:24064
	ds_read2_b32 v[132:133], v136 offset0:32 offset1:48
	s_waitcnt lgkmcnt(6)
	v_pk_mul_f32 v[36:37], v[90:91], v[114:115]
	v_pk_fma_f32 v[36:37], v[88:89], v[116:117], v[36:37]
	v_add_f32_e32 v38, v36, v37
	v_pk_mul_f32 v[40:41], v[122:123], v[130:131] op_sel:[0,1] op_sel_hi:[1,1]
	v_pk_mul_f32 v[42:43], v[124:125], v[130:131] op_sel:[0,1] op_sel_hi:[1,1]
	v_add_f32_dpp v38, v38, v38 quad_perm:[1,0,3,2] row_mask:0xf bank_mask:0xf bound_ctrl:1
	v_pk_fma_f32 v[40:41], v[90:91], v[110:111], v[40:41]
	v_pk_fma_f32 v[42:43], v[88:89], v[112:113], v[42:43]
	v_add_f32_dpp v38, v38, v38 quad_perm:[2,3,0,1] row_mask:0xf bank_mask:0xf bound_ctrl:1
	v_pk_mul_f32 v[44:45], v[90:91], v[106:107]
	v_pk_fma_f32 v[44:45], v[88:89], v[108:109], v[44:45]
	v_add_f32_dpp v38, v38, v38 row_half_mirror row_mask:0xf bank_mask:0xf bound_ctrl:1
	v_add_f32_e32 v46, v44, v45
	s_nop 0
	v_add_f32_dpp v38, v38, v38 row_mirror row_mask:0xf bank_mask:0xf bound_ctrl:1
	v_pk_fma_f32 v[90:91], v[118:119], v[38:39], v[40:41] op_sel_hi:[1,0,1]
	v_pk_fma_f32 v[88:89], v[120:121], v[38:39], v[42:43] op_sel_hi:[1,0,1]
	ds_read_b128 v[114:117], v92 offset:24576
	ds_read_b128 v[122:125], v92 offset:25088
	ds_read_b128 v[110:113], v92 offset:24320
	ds_read_b128 v[118:121], v92 offset:24832
	ds_read_b128 v[54:57], v92 offset:25344
	s_waitcnt lgkmcnt(5)
	v_pk_mul_f32 v[36:37], v[90:91], v[28:29]
	v_pk_fma_f32 v[36:37], v[88:89], v[30:31], v[36:37]
	v_add_f32_e32 v38, v36, v37
	v_pk_mul_f32 v[40:41], v[102:103], v[132:133] op_sel_hi:[1,0]
	v_pk_mul_f32 v[42:43], v[104:105], v[132:133] op_sel_hi:[1,0]
	v_add_f32_dpp v38, v38, v38 quad_perm:[1,0,3,2] row_mask:0xf bank_mask:0xf bound_ctrl:1
	v_pk_fma_f32 v[40:41], v[90:91], v[24:25], v[40:41]
	v_pk_fma_f32 v[42:43], v[88:89], v[26:27], v[42:43]
	v_add_f32_dpp v38, v38, v38 quad_perm:[2,3,0,1] row_mask:0xf bank_mask:0xf bound_ctrl:1
	v_pk_mul_f32 v[44:45], v[90:91], v[126:127]
	v_pk_fma_f32 v[44:45], v[88:89], v[128:129], v[44:45]
	v_add_f32_dpp v38, v38, v38 row_half_mirror row_mask:0xf bank_mask:0xf bound_ctrl:1
	v_add_f32_e32 v47, v44, v45
	s_nop 0
	v_add_f32_dpp v38, v38, v38 row_mirror row_mask:0xf bank_mask:0xf bound_ctrl:1
	v_pk_fma_f32 v[90:91], v[98:99], v[38:39], v[40:41] op_sel_hi:[1,0,1]
	v_pk_fma_f32 v[88:89], v[100:101], v[38:39], v[42:43] op_sel_hi:[1,0,1]
	ds_read_b128 v[28:31], v92 offset:25856
	ds_read_b128 v[102:105], v92 offset:26368
	ds_read_b128 v[24:27], v92 offset:25600
	ds_read_b128 v[98:101], v92 offset:26112
	ds_read_b128 v[106:109], v92 offset:26624
	ds_read2_b32 v[130:131], v136 offset0:64 offset1:80
	ds_write2st64_b32 v97, v46, v47 offset0:64 offset1:68
	s_waitcnt lgkmcnt(7)
	v_pk_mul_f32 v[36:37], v[90:91], v[114:115]
	v_pk_fma_f32 v[36:37], v[88:89], v[116:117], v[36:37]
	v_add_f32_e32 v38, v36, v37
	v_pk_mul_f32 v[40:41], v[122:123], v[132:133] op_sel:[0,1] op_sel_hi:[1,1]
	v_pk_mul_f32 v[42:43], v[124:125], v[132:133] op_sel:[0,1] op_sel_hi:[1,1]
	v_add_f32_dpp v38, v38, v38 quad_perm:[1,0,3,2] row_mask:0xf bank_mask:0xf bound_ctrl:1
	v_pk_fma_f32 v[40:41], v[90:91], v[110:111], v[40:41]
	v_pk_fma_f32 v[42:43], v[88:89], v[112:113], v[42:43]
	v_add_f32_dpp v38, v38, v38 quad_perm:[2,3,0,1] row_mask:0xf bank_mask:0xf bound_ctrl:1
	v_pk_mul_f32 v[44:45], v[90:91], v[50:51]
	v_pk_fma_f32 v[44:45], v[88:89], v[52:53], v[44:45]
	v_add_f32_dpp v38, v38, v38 row_half_mirror row_mask:0xf bank_mask:0xf bound_ctrl:1
	v_add_f32_e32 v48, v44, v45
	s_nop 0
	v_add_f32_dpp v38, v38, v38 row_mirror row_mask:0xf bank_mask:0xf bound_ctrl:1
	v_pk_fma_f32 v[90:91], v[118:119], v[38:39], v[40:41] op_sel_hi:[1,0,1]
	v_pk_fma_f32 v[88:89], v[120:121], v[38:39], v[42:43] op_sel_hi:[1,0,1]
	ds_read_b128 v[114:117], v92 offset:27136
	ds_read_b128 v[122:125], v92 offset:27648
	ds_read_b128 v[110:113], v92 offset:26880
	ds_read_b128 v[118:121], v92 offset:27392
	ds_read_b128 v[126:129], v92 offset:27904
	s_waitcnt lgkmcnt(5)
	v_pk_mul_f32 v[36:37], v[90:91], v[28:29]
	v_pk_fma_f32 v[36:37], v[88:89], v[30:31], v[36:37]
	v_add_f32_e32 v38, v36, v37
	v_pk_mul_f32 v[40:41], v[102:103], v[130:131] op_sel_hi:[1,0]
	v_pk_mul_f32 v[42:43], v[104:105], v[130:131] op_sel_hi:[1,0]
	v_add_f32_dpp v38, v38, v38 quad_perm:[1,0,3,2] row_mask:0xf bank_mask:0xf bound_ctrl:1
	v_pk_fma_f32 v[40:41], v[90:91], v[24:25], v[40:41]
	v_pk_fma_f32 v[42:43], v[88:89], v[26:27], v[42:43]
	v_add_f32_dpp v38, v38, v38 quad_perm:[2,3,0,1] row_mask:0xf bank_mask:0xf bound_ctrl:1
	v_pk_mul_f32 v[44:45], v[90:91], v[54:55]
	v_pk_fma_f32 v[44:45], v[88:89], v[56:57], v[44:45]
	v_add_f32_dpp v38, v38, v38 row_half_mirror row_mask:0xf bank_mask:0xf bound_ctrl:1
	v_add_f32_e32 v49, v44, v45
	s_nop 0
	v_add_f32_dpp v38, v38, v38 row_mirror row_mask:0xf bank_mask:0xf bound_ctrl:1
	v_pk_fma_f32 v[90:91], v[98:99], v[38:39], v[40:41] op_sel_hi:[1,0,1]
	v_pk_fma_f32 v[88:89], v[100:101], v[38:39], v[42:43] op_sel_hi:[1,0,1]
	ds_read_b128 v[28:31], v92 offset:28416
	ds_read_b128 v[102:105], v92 offset:28928
	ds_read_b128 v[24:27], v92 offset:28160
	ds_read_b128 v[98:101], v92 offset:28672
	ds_read_b128 v[50:53], v92 offset:29184
	ds_read2_b32 v[132:133], v136 offset0:96 offset1:112
	ds_write2st64_b32 v97, v48, v49 offset0:72 offset1:76
	s_waitcnt lgkmcnt(7)
	v_pk_mul_f32 v[36:37], v[90:91], v[114:115]
	v_pk_fma_f32 v[36:37], v[88:89], v[116:117], v[36:37]
	v_add_f32_e32 v38, v36, v37
	v_pk_mul_f32 v[40:41], v[122:123], v[130:131] op_sel:[0,1] op_sel_hi:[1,1]
	v_pk_mul_f32 v[42:43], v[124:125], v[130:131] op_sel:[0,1] op_sel_hi:[1,1]
	v_add_f32_dpp v38, v38, v38 quad_perm:[1,0,3,2] row_mask:0xf bank_mask:0xf bound_ctrl:1
	v_pk_fma_f32 v[40:41], v[90:91], v[110:111], v[40:41]
	v_pk_fma_f32 v[42:43], v[88:89], v[112:113], v[42:43]
	v_add_f32_dpp v38, v38, v38 quad_perm:[2,3,0,1] row_mask:0xf bank_mask:0xf bound_ctrl:1
	v_pk_mul_f32 v[44:45], v[90:91], v[106:107]
	v_pk_fma_f32 v[44:45], v[88:89], v[108:109], v[44:45]
	v_add_f32_dpp v38, v38, v38 row_half_mirror row_mask:0xf bank_mask:0xf bound_ctrl:1
	v_add_f32_e32 v46, v44, v45
	s_nop 0
	v_add_f32_dpp v38, v38, v38 row_mirror row_mask:0xf bank_mask:0xf bound_ctrl:1
	v_pk_fma_f32 v[90:91], v[118:119], v[38:39], v[40:41] op_sel_hi:[1,0,1]
	v_pk_fma_f32 v[88:89], v[120:121], v[38:39], v[42:43] op_sel_hi:[1,0,1]
	ds_read_b128 v[114:117], v92 offset:29696
	ds_read_b128 v[122:125], v92 offset:30208
	ds_read_b128 v[110:113], v92 offset:29440
	ds_read_b128 v[118:121], v92 offset:29952
	ds_read_b128 v[54:57], v92 offset:30464
	s_waitcnt lgkmcnt(5)
	v_pk_mul_f32 v[36:37], v[90:91], v[28:29]
	v_pk_fma_f32 v[36:37], v[88:89], v[30:31], v[36:37]
	v_add_f32_e32 v38, v36, v37
	v_pk_mul_f32 v[40:41], v[102:103], v[132:133] op_sel_hi:[1,0]
	v_pk_mul_f32 v[42:43], v[104:105], v[132:133] op_sel_hi:[1,0]
	v_add_f32_dpp v38, v38, v38 quad_perm:[1,0,3,2] row_mask:0xf bank_mask:0xf bound_ctrl:1
	v_pk_fma_f32 v[40:41], v[90:91], v[24:25], v[40:41]
	v_pk_fma_f32 v[42:43], v[88:89], v[26:27], v[42:43]
	v_add_f32_dpp v38, v38, v38 quad_perm:[2,3,0,1] row_mask:0xf bank_mask:0xf bound_ctrl:1
	v_pk_mul_f32 v[44:45], v[90:91], v[126:127]
	v_pk_fma_f32 v[44:45], v[88:89], v[128:129], v[44:45]
	v_add_f32_dpp v38, v38, v38 row_half_mirror row_mask:0xf bank_mask:0xf bound_ctrl:1
	v_add_f32_e32 v47, v44, v45
	s_nop 0
	v_add_f32_dpp v38, v38, v38 row_mirror row_mask:0xf bank_mask:0xf bound_ctrl:1
	v_pk_fma_f32 v[90:91], v[98:99], v[38:39], v[40:41] op_sel_hi:[1,0,1]
	v_pk_fma_f32 v[88:89], v[100:101], v[38:39], v[42:43] op_sel_hi:[1,0,1]
	ds_read_b128 v[28:31], v92 offset:30976
	ds_read_b128 v[102:105], v92 offset:31488
	ds_read_b128 v[24:27], v92 offset:30720
	ds_read_b128 v[98:101], v92 offset:31232
	ds_read_b128 v[106:109], v92 offset:31744
	ds_read2_b32 v[130:131], v136 offset0:128 offset1:144
	ds_write2st64_b32 v97, v46, v47 offset0:80 offset1:84
	s_waitcnt lgkmcnt(7)
	v_pk_mul_f32 v[36:37], v[90:91], v[114:115]
	v_pk_fma_f32 v[36:37], v[88:89], v[116:117], v[36:37]
	v_add_f32_e32 v38, v36, v37
	v_pk_mul_f32 v[40:41], v[122:123], v[132:133] op_sel:[0,1] op_sel_hi:[1,1]
	v_pk_mul_f32 v[42:43], v[124:125], v[132:133] op_sel:[0,1] op_sel_hi:[1,1]
	v_add_f32_dpp v38, v38, v38 quad_perm:[1,0,3,2] row_mask:0xf bank_mask:0xf bound_ctrl:1
	v_pk_fma_f32 v[40:41], v[90:91], v[110:111], v[40:41]
	v_pk_fma_f32 v[42:43], v[88:89], v[112:113], v[42:43]
	v_add_f32_dpp v38, v38, v38 quad_perm:[2,3,0,1] row_mask:0xf bank_mask:0xf bound_ctrl:1
	v_pk_mul_f32 v[44:45], v[90:91], v[50:51]
	v_pk_fma_f32 v[44:45], v[88:89], v[52:53], v[44:45]
	v_add_f32_dpp v38, v38, v38 row_half_mirror row_mask:0xf bank_mask:0xf bound_ctrl:1
	v_add_f32_e32 v48, v44, v45
	s_nop 0
	v_add_f32_dpp v38, v38, v38 row_mirror row_mask:0xf bank_mask:0xf bound_ctrl:1
	v_pk_fma_f32 v[90:91], v[118:119], v[38:39], v[40:41] op_sel_hi:[1,0,1]
	v_pk_fma_f32 v[88:89], v[120:121], v[38:39], v[42:43] op_sel_hi:[1,0,1]
	ds_read_b128 v[114:117], v92 offset:32256
	ds_read_b128 v[122:125], v92 offset:32768
	ds_read_b128 v[110:113], v92 offset:32000
	ds_read_b128 v[118:121], v92 offset:32512
	ds_read_b128 v[126:129], v92 offset:33024
	s_waitcnt lgkmcnt(5)
	v_pk_mul_f32 v[36:37], v[90:91], v[28:29]
	v_pk_fma_f32 v[36:37], v[88:89], v[30:31], v[36:37]
	v_add_f32_e32 v38, v36, v37
	v_pk_mul_f32 v[40:41], v[102:103], v[130:131] op_sel_hi:[1,0]
	v_pk_mul_f32 v[42:43], v[104:105], v[130:131] op_sel_hi:[1,0]
	v_add_f32_dpp v38, v38, v38 quad_perm:[1,0,3,2] row_mask:0xf bank_mask:0xf bound_ctrl:1
	v_pk_fma_f32 v[40:41], v[90:91], v[24:25], v[40:41]
	v_pk_fma_f32 v[42:43], v[88:89], v[26:27], v[42:43]
	v_add_f32_dpp v38, v38, v38 quad_perm:[2,3,0,1] row_mask:0xf bank_mask:0xf bound_ctrl:1
	v_pk_mul_f32 v[44:45], v[90:91], v[54:55]
	v_pk_fma_f32 v[44:45], v[88:89], v[56:57], v[44:45]
	v_add_f32_dpp v38, v38, v38 row_half_mirror row_mask:0xf bank_mask:0xf bound_ctrl:1
	v_add_f32_e32 v49, v44, v45
	s_nop 0
	v_add_f32_dpp v38, v38, v38 row_mirror row_mask:0xf bank_mask:0xf bound_ctrl:1
	v_pk_fma_f32 v[90:91], v[98:99], v[38:39], v[40:41] op_sel_hi:[1,0,1]
	v_pk_fma_f32 v[88:89], v[100:101], v[38:39], v[42:43] op_sel_hi:[1,0,1]
	ds_read_b128 v[28:31], v92 offset:33536
	ds_read_b128 v[102:105], v92 offset:34048
	ds_read_b128 v[24:27], v92 offset:33280
	ds_read_b128 v[98:101], v92 offset:33792
	ds_read_b128 v[50:53], v92 offset:34304
	ds_read2_b32 v[132:133], v136 offset0:160 offset1:176
	ds_write2st64_b32 v97, v48, v49 offset0:88 offset1:92
	s_waitcnt lgkmcnt(7)
	v_pk_mul_f32 v[36:37], v[90:91], v[114:115]
	v_pk_fma_f32 v[36:37], v[88:89], v[116:117], v[36:37]
	v_add_f32_e32 v38, v36, v37
	v_pk_mul_f32 v[40:41], v[122:123], v[130:131] op_sel:[0,1] op_sel_hi:[1,1]
	v_pk_mul_f32 v[42:43], v[124:125], v[130:131] op_sel:[0,1] op_sel_hi:[1,1]
	v_add_f32_dpp v38, v38, v38 quad_perm:[1,0,3,2] row_mask:0xf bank_mask:0xf bound_ctrl:1
	v_pk_fma_f32 v[40:41], v[90:91], v[110:111], v[40:41]
	v_pk_fma_f32 v[42:43], v[88:89], v[112:113], v[42:43]
	v_add_f32_dpp v38, v38, v38 quad_perm:[2,3,0,1] row_mask:0xf bank_mask:0xf bound_ctrl:1
	v_pk_mul_f32 v[44:45], v[90:91], v[106:107]
	v_pk_fma_f32 v[44:45], v[88:89], v[108:109], v[44:45]
	v_add_f32_dpp v38, v38, v38 row_half_mirror row_mask:0xf bank_mask:0xf bound_ctrl:1
	v_add_f32_e32 v46, v44, v45
	s_nop 0
	v_add_f32_dpp v38, v38, v38 row_mirror row_mask:0xf bank_mask:0xf bound_ctrl:1
	v_pk_fma_f32 v[90:91], v[118:119], v[38:39], v[40:41] op_sel_hi:[1,0,1]
	v_pk_fma_f32 v[88:89], v[120:121], v[38:39], v[42:43] op_sel_hi:[1,0,1]
	ds_read_b128 v[114:117], v92 offset:34816
	ds_read_b128 v[122:125], v92 offset:35328
	ds_read_b128 v[110:113], v92 offset:34560
	ds_read_b128 v[118:121], v92 offset:35072
	ds_read_b128 v[54:57], v92 offset:35584
	s_waitcnt lgkmcnt(5)
	v_pk_mul_f32 v[36:37], v[90:91], v[28:29]
	v_pk_fma_f32 v[36:37], v[88:89], v[30:31], v[36:37]
	v_add_f32_e32 v38, v36, v37
	v_pk_mul_f32 v[40:41], v[102:103], v[132:133] op_sel_hi:[1,0]
	v_pk_mul_f32 v[42:43], v[104:105], v[132:133] op_sel_hi:[1,0]
	v_add_f32_dpp v38, v38, v38 quad_perm:[1,0,3,2] row_mask:0xf bank_mask:0xf bound_ctrl:1
	v_pk_fma_f32 v[40:41], v[90:91], v[24:25], v[40:41]
	v_pk_fma_f32 v[42:43], v[88:89], v[26:27], v[42:43]
	v_add_f32_dpp v38, v38, v38 quad_perm:[2,3,0,1] row_mask:0xf bank_mask:0xf bound_ctrl:1
	v_pk_mul_f32 v[44:45], v[90:91], v[126:127]
	v_pk_fma_f32 v[44:45], v[88:89], v[128:129], v[44:45]
	v_add_f32_dpp v38, v38, v38 row_half_mirror row_mask:0xf bank_mask:0xf bound_ctrl:1
	v_add_f32_e32 v47, v44, v45
	s_nop 0
	v_add_f32_dpp v38, v38, v38 row_mirror row_mask:0xf bank_mask:0xf bound_ctrl:1
	v_pk_fma_f32 v[90:91], v[98:99], v[38:39], v[40:41] op_sel_hi:[1,0,1]
	v_pk_fma_f32 v[88:89], v[100:101], v[38:39], v[42:43] op_sel_hi:[1,0,1]
	ds_read_b128 v[28:31], v92 offset:36096
	ds_read_b128 v[102:105], v92 offset:36608
	ds_read_b128 v[24:27], v92 offset:35840
	ds_read_b128 v[98:101], v92 offset:36352
	ds_read_b128 v[106:109], v92 offset:36864
	ds_read2_b32 v[130:131], v136 offset0:192 offset1:208
	ds_write2st64_b32 v97, v46, v47 offset0:96 offset1:100
	s_waitcnt lgkmcnt(7)
	v_pk_mul_f32 v[36:37], v[90:91], v[114:115]
	v_pk_fma_f32 v[36:37], v[88:89], v[116:117], v[36:37]
	v_add_f32_e32 v38, v36, v37
	v_pk_mul_f32 v[40:41], v[122:123], v[132:133] op_sel:[0,1] op_sel_hi:[1,1]
	v_pk_mul_f32 v[42:43], v[124:125], v[132:133] op_sel:[0,1] op_sel_hi:[1,1]
	v_add_f32_dpp v38, v38, v38 quad_perm:[1,0,3,2] row_mask:0xf bank_mask:0xf bound_ctrl:1
	v_pk_fma_f32 v[40:41], v[90:91], v[110:111], v[40:41]
	v_pk_fma_f32 v[42:43], v[88:89], v[112:113], v[42:43]
	v_add_f32_dpp v38, v38, v38 quad_perm:[2,3,0,1] row_mask:0xf bank_mask:0xf bound_ctrl:1
	v_pk_mul_f32 v[44:45], v[90:91], v[50:51]
	v_pk_fma_f32 v[44:45], v[88:89], v[52:53], v[44:45]
	v_add_f32_dpp v38, v38, v38 row_half_mirror row_mask:0xf bank_mask:0xf bound_ctrl:1
	v_add_f32_e32 v48, v44, v45
	s_nop 0
	v_add_f32_dpp v38, v38, v38 row_mirror row_mask:0xf bank_mask:0xf bound_ctrl:1
	v_pk_fma_f32 v[90:91], v[118:119], v[38:39], v[40:41] op_sel_hi:[1,0,1]
	v_pk_fma_f32 v[88:89], v[120:121], v[38:39], v[42:43] op_sel_hi:[1,0,1]
	ds_read_b128 v[114:117], v92 offset:37376
	ds_read_b128 v[122:125], v92 offset:37888
	ds_read_b128 v[110:113], v92 offset:37120
	ds_read_b128 v[118:121], v92 offset:37632
	ds_read_b128 v[126:129], v92 offset:38144
	s_waitcnt lgkmcnt(5)
	v_pk_mul_f32 v[36:37], v[90:91], v[28:29]
	v_pk_fma_f32 v[36:37], v[88:89], v[30:31], v[36:37]
	v_add_f32_e32 v38, v36, v37
	v_pk_mul_f32 v[40:41], v[102:103], v[130:131] op_sel_hi:[1,0]
	v_pk_mul_f32 v[42:43], v[104:105], v[130:131] op_sel_hi:[1,0]
	v_add_f32_dpp v38, v38, v38 quad_perm:[1,0,3,2] row_mask:0xf bank_mask:0xf bound_ctrl:1
	v_pk_fma_f32 v[40:41], v[90:91], v[24:25], v[40:41]
	v_pk_fma_f32 v[42:43], v[88:89], v[26:27], v[42:43]
	v_add_f32_dpp v38, v38, v38 quad_perm:[2,3,0,1] row_mask:0xf bank_mask:0xf bound_ctrl:1
	v_pk_mul_f32 v[44:45], v[90:91], v[54:55]
	v_pk_fma_f32 v[44:45], v[88:89], v[56:57], v[44:45]
	v_add_f32_dpp v38, v38, v38 row_half_mirror row_mask:0xf bank_mask:0xf bound_ctrl:1
	v_add_f32_e32 v49, v44, v45
	s_nop 0
	v_add_f32_dpp v38, v38, v38 row_mirror row_mask:0xf bank_mask:0xf bound_ctrl:1
	v_pk_fma_f32 v[90:91], v[98:99], v[38:39], v[40:41] op_sel_hi:[1,0,1]
	v_pk_fma_f32 v[88:89], v[100:101], v[38:39], v[42:43] op_sel_hi:[1,0,1]
	ds_read_b128 v[28:31], v92 offset:38656
	ds_read_b128 v[102:105], v92 offset:39168
	ds_read_b128 v[24:27], v92 offset:38400
	ds_read_b128 v[98:101], v92 offset:38912
	ds_read_b128 v[50:53], v92 offset:39424
	ds_read2_b32 v[132:133], v136 offset0:224 offset1:240
	ds_write2st64_b32 v97, v48, v49 offset0:104 offset1:108
	s_waitcnt lgkmcnt(7)
	v_pk_mul_f32 v[36:37], v[90:91], v[114:115]
	v_pk_fma_f32 v[36:37], v[88:89], v[116:117], v[36:37]
	v_add_f32_e32 v38, v36, v37
	v_pk_mul_f32 v[40:41], v[122:123], v[130:131] op_sel:[0,1] op_sel_hi:[1,1]
	v_pk_mul_f32 v[42:43], v[124:125], v[130:131] op_sel:[0,1] op_sel_hi:[1,1]
	v_add_f32_dpp v38, v38, v38 quad_perm:[1,0,3,2] row_mask:0xf bank_mask:0xf bound_ctrl:1
	v_pk_fma_f32 v[40:41], v[90:91], v[110:111], v[40:41]
	v_pk_fma_f32 v[42:43], v[88:89], v[112:113], v[42:43]
	v_add_f32_dpp v38, v38, v38 quad_perm:[2,3,0,1] row_mask:0xf bank_mask:0xf bound_ctrl:1
	v_pk_mul_f32 v[44:45], v[90:91], v[106:107]
	v_pk_fma_f32 v[44:45], v[88:89], v[108:109], v[44:45]
	v_add_f32_dpp v38, v38, v38 row_half_mirror row_mask:0xf bank_mask:0xf bound_ctrl:1
	v_add_f32_e32 v46, v44, v45
	s_nop 0
	v_add_f32_dpp v38, v38, v38 row_mirror row_mask:0xf bank_mask:0xf bound_ctrl:1
	v_pk_fma_f32 v[90:91], v[118:119], v[38:39], v[40:41] op_sel_hi:[1,0,1]
	v_pk_fma_f32 v[88:89], v[120:121], v[38:39], v[42:43] op_sel_hi:[1,0,1]
	ds_read_b128 v[114:117], v92 offset:39936
	ds_read_b128 v[122:125], v92 offset:40448
	ds_read_b128 v[110:113], v92 offset:39680
	ds_read_b128 v[118:121], v92 offset:40192
	ds_read_b128 v[54:57], v92 offset:40704
	s_waitcnt lgkmcnt(5)
	v_pk_mul_f32 v[36:37], v[90:91], v[28:29]
	v_pk_fma_f32 v[36:37], v[88:89], v[30:31], v[36:37]
	v_add_f32_e32 v38, v36, v37
	v_pk_mul_f32 v[40:41], v[102:103], v[132:133] op_sel_hi:[1,0]
	v_pk_mul_f32 v[42:43], v[104:105], v[132:133] op_sel_hi:[1,0]
	v_add_f32_dpp v38, v38, v38 quad_perm:[1,0,3,2] row_mask:0xf bank_mask:0xf bound_ctrl:1
	v_pk_fma_f32 v[40:41], v[90:91], v[24:25], v[40:41]
	v_pk_fma_f32 v[42:43], v[88:89], v[26:27], v[42:43]
	v_add_f32_dpp v38, v38, v38 quad_perm:[2,3,0,1] row_mask:0xf bank_mask:0xf bound_ctrl:1
	v_pk_mul_f32 v[44:45], v[90:91], v[126:127]
	v_pk_fma_f32 v[44:45], v[88:89], v[128:129], v[44:45]
	v_add_f32_dpp v38, v38, v38 row_half_mirror row_mask:0xf bank_mask:0xf bound_ctrl:1
	v_add_f32_e32 v47, v44, v45
	s_nop 0
	v_add_f32_dpp v38, v38, v38 row_mirror row_mask:0xf bank_mask:0xf bound_ctrl:1
	v_pk_fma_f32 v[90:91], v[98:99], v[38:39], v[40:41] op_sel_hi:[1,0,1]
	v_pk_fma_f32 v[88:89], v[100:101], v[38:39], v[42:43] op_sel_hi:[1,0,1]
	ds_write2st64_b32 v97, v46, v47 offset0:112 offset1:116
	s_waitcnt lgkmcnt(1)
	v_pk_mul_f32 v[36:37], v[90:91], v[114:115]
	v_pk_fma_f32 v[36:37], v[88:89], v[116:117], v[36:37]
	v_add_f32_e32 v38, v36, v37
	v_pk_mul_f32 v[40:41], v[122:123], v[132:133] op_sel:[0,1] op_sel_hi:[1,1]
	v_pk_mul_f32 v[42:43], v[124:125], v[132:133] op_sel:[0,1] op_sel_hi:[1,1]
	v_add_f32_dpp v38, v38, v38 quad_perm:[1,0,3,2] row_mask:0xf bank_mask:0xf bound_ctrl:1
	v_pk_fma_f32 v[40:41], v[90:91], v[110:111], v[40:41]
	v_pk_fma_f32 v[42:43], v[88:89], v[112:113], v[42:43]
	v_add_f32_dpp v38, v38, v38 quad_perm:[2,3,0,1] row_mask:0xf bank_mask:0xf bound_ctrl:1
	v_pk_mul_f32 v[44:45], v[90:91], v[50:51]
	v_pk_fma_f32 v[44:45], v[88:89], v[52:53], v[44:45]
	v_add_f32_dpp v38, v38, v38 row_half_mirror row_mask:0xf bank_mask:0xf bound_ctrl:1
	v_add_f32_e32 v48, v44, v45
	s_nop 0
	v_add_f32_dpp v38, v38, v38 row_mirror row_mask:0xf bank_mask:0xf bound_ctrl:1
	v_pk_fma_f32 v[90:91], v[118:119], v[38:39], v[40:41] op_sel_hi:[1,0,1]
	v_pk_fma_f32 v[88:89], v[120:121], v[38:39], v[42:43] op_sel_hi:[1,0,1]
	v_pk_mul_f32 v[44:45], v[90:91], v[54:55]
	v_pk_fma_f32 v[44:45], v[88:89], v[56:57], v[44:45]
	v_add_f32_e32 v49, v44, v45
	ds_write2st64_b32 v97, v48, v49 offset0:120 offset1:124
	s_branch .LBB0_640
